# ssm_s2 (X2 stragglers, 8 workgroups): software-prefetch next iteration's 8 chunk-state loads (double register set)
# speedup vs baseline: 1.0017x; 1.0017x over previous
; DI void sincos_acc(float ang, float& c, float& s) { double rev = (double)ang * 0.15915494309189535; rev -= __builtin_rint(rev); const float r = (float)rev; s = __builtin_amdgcn_sinf(r); c = __builtin_amdgcn_cosf(r); }
; DI void ssm_consts(CArgs& a, int l, int g, int n, SsmC& c) {
;     const int gi = (l * 32 + g) * 64 + n;
;     const float lr = a.in[I_ARE][gi], li = a.in[I_AIM][gi], dt = expf(a.in[I_LOGDT][l * 32 + g]);
;     const float mag = expf(lr * dt); float cs, sn; sincos_acc(li * dt, cs, sn);
;     c.ar = mag * cs; c.ai = mag * sn;
;     const float den = lr * lr + li * li, nr = c.ar - 1.f, ni = c.ai;
;     const float zr = (nr * lr + ni * li) / den, zi = (ni * lr - nr * li) / den;
; DI void ssm_s2(CArgs& a, int l, int id) {
;     const int n = id & 63, g = (id >> 6) & 31, b = id >> 11;
;     SsmC c; ssm_consts(a, l, g, n, c);
;     float pr = c.ar, pi = c.ai;
; #pragma unroll
;     for (int q = 0; q < 7; ++q) { const float tr = pr * pr - pi * pi, ti = 2.f * pr * pi; pr = tr; pi = ti; }
;     const f32x2* xl = (const f32x2*)(a.ws + WS_XLOC); f32x2* xin = (f32x2*)(a.ws + WS_XIN);
;     float xr = 0.f, xi = 0.f;
;     for (int c0 = 0; c0 < 128; c0 += 8) {
;         f32x2 v[8];
; #pragma unroll
;         for (int j = 0; j < 8; ++j) v[j] = xl[(size_t)((b * 128 + c0 + j) * 32 + g) * 64 + n];
.LBB0_423:
	v_bfe_u32 v10, v42, 6, 5
	v_readlane_b32 s0, v253, 15
	v_mov_b32_e32 v5, v81
	s_mov_b32 s4, 0x42b17218
	v_or_b32_e32 v4, s0, v10
	s_load_dwordx2 s[0:1], s[94:95], 0x88
	v_lshl_or_b32 v80, v4, 6, v186
	v_lshlrev_b64 v[6:7], 2, v[80:81]
	s_waitcnt lgkmcnt(0)
	v_lshl_add_u64 v[8:9], s[8:9], 0, v[6:7]
	global_load_dword v8, v[8:9], off
	v_lshl_add_u64 v[4:5], v[4:5], 2, s[0:1]
	global_load_dword v5, v[4:5], off
	v_lshl_add_u64 v[6:7], s[10:11], 0, v[6:7]
	global_load_dword v6, v[6:7], off
	s_mov_b32 s0, 0x3fb8aa3b
	s_mov_b32 s1, 0xc2ce8ed0
	s_waitcnt vmcnt(1)
	v_mul_f32_e32 v4, 0x3fb8aa3b, v5
	v_fma_f32 v7, v5, s0, -v4
	v_rndne_f32_e32 v9, v4
	v_fmac_f32_e32 v7, 0x32a5705f, v5
	v_sub_f32_e32 v4, v4, v9
	v_add_f32_e32 v4, v4, v7
	v_exp_f32_e32 v4, v4
	v_cvt_i32_f32_e32 v7, v9
	v_cmp_ngt_f32_e32 vcc, s1, v5
	v_ldexp_f32 v7, v4, v7
	s_nop 0
	v_cndmask_b32_e32 v7, 0, v7, vcc
	v_cmp_nlt_f32_e32 vcc, s4, v5
	v_mov_b32_e32 v4, 0
	s_nop 0
	v_cndmask_b32_e32 v5, v221, v7, vcc
	v_mul_f32_e32 v7, v8, v5
	v_mul_f32_e32 v8, 0x3fb8aa3b, v7
	v_fma_f32 v9, v7, s0, -v8
	v_rndne_f32_e32 v11, v8
	v_fmac_f32_e32 v9, 0x32a5705f, v7
	v_sub_f32_e32 v8, v8, v11
	v_add_f32_e32 v8, v8, v9
	v_exp_f32_e32 v8, v8
	v_cvt_i32_f32_e32 v9, v11
	v_cmp_ngt_f32_e32 vcc, s1, v7
	s_waitcnt vmcnt(0)
	v_mul_f32_e32 v5, v6, v5
	s_mov_b32 s0, 0x6dc9c883
	v_ldexp_f32 v8, v8, v9
	v_cndmask_b32_e32 v8, 0, v8, vcc
	v_cmp_nlt_f32_e32 vcc, s4, v7
	v_cvt_f64_f32_e32 v[6:7], v5
	s_mov_b32 s1, 0x3fc45f30
	v_cndmask_b32_e32 v11, v221, v8, vcc
	v_mul_f64 v[8:9], v[6:7], s[0:1]
	v_rndne_f64_e32 v[8:9], v[8:9]
	v_fma_f64 v[6:7], v[6:7], s[0:1], -v[8:9]
	v_cvt_f32_f64_e32 v5, v[6:7]
	v_sin_f32_e32 v6, v5
	v_cos_f32_e32 v5, v5
	s_movk_i32 s0, 0xe0
	v_mul_f32_e32 v6, v11, v6
	v_mul_f32_e32 v5, v11, v5
	v_mul_f32_e32 v7, v6, v6
	v_fma_f32 v7, v5, v5, -v7
	v_add_f32_e32 v5, v5, v5
	v_mul_f32_e32 v5, v6, v5
	v_mul_f32_e32 v6, v5, v5
	v_fma_f32 v6, v7, v7, -v6
	v_add_f32_e32 v7, v7, v7
	v_mul_f32_e32 v5, v5, v7
	v_mul_f32_e32 v7, v5, v5
	v_fma_f32 v7, v6, v6, -v7
	v_add_f32_e32 v6, v6, v6
	v_mul_f32_e32 v5, v5, v6
	v_mul_f32_e32 v6, v5, v5
	v_fma_f32 v6, v7, v7, -v6
	v_add_f32_e32 v7, v7, v7
	v_mul_f32_e32 v5, v5, v7
	v_mul_f32_e32 v7, v5, v5
	v_fma_f32 v7, v6, v6, -v7
	v_add_f32_e32 v6, v6, v6
	v_mul_f32_e32 v5, v5, v6
	v_mul_f32_e32 v6, v5, v5
	v_fma_f32 v8, v7, v7, -v6
	v_add_f32_e32 v6, v7, v7
	v_mul_f32_e32 v5, v5, v6
	v_mul_f32_e32 v6, v5, v5
	v_add_f32_e32 v7, v8, v8
	v_fma_f32 v6, v8, v8, -v6
	v_mul_f32_e32 v8, v5, v7
	v_lshlrev_b32_e32 v5, 1, v42
	v_and_b32_e32 v5, 0xfffff000, v5
	v_mov_b32_e32 v7, v6
	v_mov_b32_e32 v9, v8
	v_or3_b32 v10, v5, v10, s0
	s_mov_b32 s0, -8
	v_mov_b32_e32 v5, v4
	v_add_u32_e32 v248, 0xffffff20, v10
	v_ashrrev_i32_e32 v249, 31, v248
	v_lshlrev_b64 v[248:249], 9, v[248:249]
	v_lshl_add_u64 v[248:249], v[0:1], 0, v[248:249]
	global_load_dwordx2 v[232:233], v[248:249], off
	v_add_u32_e32 v248, 0xffffff40, v10
	v_ashrrev_i32_e32 v249, 31, v248
	v_lshlrev_b64 v[248:249], 9, v[248:249]
	v_lshl_add_u64 v[248:249], v[0:1], 0, v[248:249]
	global_load_dwordx2 v[234:235], v[248:249], off
	v_add_u32_e32 v248, 0xffffff60, v10
	v_ashrrev_i32_e32 v249, 31, v248
	v_lshlrev_b64 v[248:249], 9, v[248:249]
	v_lshl_add_u64 v[248:249], v[0:1], 0, v[248:249]
	global_load_dwordx2 v[236:237], v[248:249], off
	v_add_u32_e32 v248, 0xffffff80, v10
	v_ashrrev_i32_e32 v249, 31, v248
	v_lshlrev_b64 v[248:249], 9, v[248:249]
	v_lshl_add_u64 v[248:249], v[0:1], 0, v[248:249]
	global_load_dwordx2 v[238:239], v[248:249], off
	v_add_u32_e32 v248, 0xffffffa0, v10
	v_ashrrev_i32_e32 v249, 31, v248
	v_lshlrev_b64 v[248:249], 9, v[248:249]
	v_lshl_add_u64 v[248:249], v[0:1], 0, v[248:249]
	global_load_dwordx2 v[240:241], v[248:249], off
	v_add_u32_e32 v248, 0xffffffc0, v10
	v_ashrrev_i32_e32 v249, 31, v248
	v_lshlrev_b64 v[248:249], 9, v[248:249]
	v_lshl_add_u64 v[248:249], v[0:1], 0, v[248:249]
	global_load_dwordx2 v[242:243], v[248:249], off
	v_add_u32_e32 v248, 0xffffffe0, v10
	v_ashrrev_i32_e32 v249, 31, v248
	v_lshlrev_b64 v[248:249], 9, v[248:249]
	v_lshl_add_u64 v[248:249], v[0:1], 0, v[248:249]
	global_load_dwordx2 v[244:245], v[248:249], off
	v_add_u32_e32 v248, 0, v10
	v_ashrrev_i32_e32 v249, 31, v248
	v_lshlrev_b64 v[248:249], 9, v[248:249]
	v_lshl_add_u64 v[248:249], v[0:1], 0, v[248:249]
	global_load_dwordx2 v[246:247], v[248:249], off
	s_waitcnt vmcnt(0)
; DI void ssm_s2(CArgs& a, int l, int id) {
;     ...
;     for (int c0 = 0; c0 < 128; c0 += 8) {
;         f32x2 v[8];
; #pragma unroll
;         for (int j = 0; j < 8; ++j) v[j] = xl[(size_t)((b * 128 + c0 + j) * 32 + g) * 64 + n];
; #pragma unroll
;         for (int j = 0; j < 8; ++j) { xin[(size_t)((b * 128 + c0 + j) * 32 + g) * 64 + n] = (f32x2){xr, xi};
;             const float nxr = pr * xr - pi * xi + v[j].x, nxi = pr * xi + pi * xr + v[j].y; xr = nxr; xi = nxi; }
;     }
.LBB0_424:
	v_add_u32_e32 v12, 0xffffff20, v10
	v_ashrrev_i32_e32 v13, 31, v12
	v_lshlrev_b64 v[14:15], 9, v[12:13]
	v_lshl_add_u64 v[12:13], v[0:1], 0, v[14:15]
	v_add_u32_e32 v16, 0xffffff40, v10
	v_ashrrev_i32_e32 v17, 31, v16
	v_lshlrev_b64 v[16:17], 9, v[16:17]
	v_lshl_add_u64 v[18:19], v[0:1], 0, v[16:17]
	v_add_u32_e32 v20, 0xffffff60, v10
	v_ashrrev_i32_e32 v21, 31, v20
	v_lshlrev_b64 v[20:21], 9, v[20:21]
	v_lshl_add_u64 v[22:23], v[0:1], 0, v[20:21]
	v_add_u32_e32 v24, 0xffffff80, v10
	v_ashrrev_i32_e32 v25, 31, v24
	v_lshlrev_b64 v[24:25], 9, v[24:25]
	v_lshl_add_u64 v[26:27], v[0:1], 0, v[24:25]
	v_add_u32_e32 v28, 0xffffffa0, v10
	v_ashrrev_i32_e32 v29, 31, v28
	v_lshlrev_b64 v[28:29], 9, v[28:29]
	v_lshl_add_u64 v[30:31], v[0:1], 0, v[28:29]
	v_subrev_u32_e32 v32, 64, v10
	v_ashrrev_i32_e32 v33, 31, v32
	v_lshlrev_b64 v[32:33], 9, v[32:33]
	v_lshl_add_u64 v[34:35], v[0:1], 0, v[32:33]
	v_subrev_u32_e32 v36, 32, v10
	v_ashrrev_i32_e32 v37, 31, v36
	v_lshlrev_b64 v[36:37], 9, v[36:37]
	v_lshl_add_u64 v[38:39], v[0:1], 0, v[36:37]
	v_ashrrev_i32_e32 v11, 31, v10
	v_lshlrev_b64 v[40:41], 9, v[10:11]
	v_lshl_add_u64 v[44:45], v[0:1], 0, v[40:41]
	s_waitcnt vmcnt(8)
	v_mov_b32_e32 v12, v232
	v_mov_b32_e32 v13, v233
	v_mov_b32_e32 v18, v234
	v_mov_b32_e32 v19, v235
	v_mov_b32_e32 v22, v236
	v_mov_b32_e32 v23, v237
	v_mov_b32_e32 v26, v238
	v_mov_b32_e32 v27, v239
	v_mov_b32_e32 v30, v240
	v_mov_b32_e32 v31, v241
	v_mov_b32_e32 v34, v242
	v_mov_b32_e32 v35, v243
	v_mov_b32_e32 v38, v244
	v_mov_b32_e32 v39, v245
	v_mov_b32_e32 v44, v246
	v_mov_b32_e32 v45, v247
	v_add_u32_e32 v248, 32, v10
	v_ashrrev_i32_e32 v249, 31, v248
	v_lshlrev_b64 v[248:249], 9, v[248:249]
	v_lshl_add_u64 v[248:249], v[0:1], 0, v[248:249]
	global_load_dwordx2 v[232:233], v[248:249], off
	v_add_u32_e32 v248, 64, v10
	v_ashrrev_i32_e32 v249, 31, v248
	v_lshlrev_b64 v[248:249], 9, v[248:249]
	v_lshl_add_u64 v[248:249], v[0:1], 0, v[248:249]
	global_load_dwordx2 v[234:235], v[248:249], off
	v_add_u32_e32 v248, 0x60, v10
	v_ashrrev_i32_e32 v249, 31, v248
	v_lshlrev_b64 v[248:249], 9, v[248:249]
	v_lshl_add_u64 v[248:249], v[0:1], 0, v[248:249]
	global_load_dwordx2 v[236:237], v[248:249], off
	v_add_u32_e32 v248, 0x80, v10
	v_ashrrev_i32_e32 v249, 31, v248
	v_lshlrev_b64 v[248:249], 9, v[248:249]
	v_lshl_add_u64 v[248:249], v[0:1], 0, v[248:249]
	global_load_dwordx2 v[238:239], v[248:249], off
	v_add_u32_e32 v248, 0xa0, v10
	v_ashrrev_i32_e32 v249, 31, v248
	v_lshlrev_b64 v[248:249], 9, v[248:249]
	v_lshl_add_u64 v[248:249], v[0:1], 0, v[248:249]
	global_load_dwordx2 v[240:241], v[248:249], off
	v_add_u32_e32 v248, 0xc0, v10
	v_ashrrev_i32_e32 v249, 31, v248
	v_lshlrev_b64 v[248:249], 9, v[248:249]
	v_lshl_add_u64 v[248:249], v[0:1], 0, v[248:249]
	global_load_dwordx2 v[242:243], v[248:249], off
	v_add_u32_e32 v248, 0xe0, v10
	v_ashrrev_i32_e32 v249, 31, v248
	v_lshlrev_b64 v[248:249], 9, v[248:249]
	v_lshl_add_u64 v[248:249], v[0:1], 0, v[248:249]
	global_load_dwordx2 v[244:245], v[248:249], off
	v_add_u32_e32 v248, 0x100, v10
	v_ashrrev_i32_e32 v249, 31, v248
	v_lshlrev_b64 v[248:249], 9, v[248:249]
	v_lshl_add_u64 v[248:249], v[0:1], 0, v[248:249]
	global_load_dwordx2 v[246:247], v[248:249], off
	v_lshl_add_u64 v[14:15], v[2:3], 0, v[14:15]
	global_store_dwordx2 v[14:15], v[4:5], off
	v_pk_mul_f32 v[14:15], v[8:9], v[4:5]
	s_add_i32 s0, s0, 8
	v_pk_fma_f32 v[46:47], v[6:7], v[4:5], v[14:15] op_sel:[0,0,1] op_sel_hi:[1,1,0] neg_lo:[0,0,1] neg_hi:[0,0,1]
	v_pk_fma_f32 v[4:5], v[6:7], v[4:5], v[14:15] op_sel:[0,0,1] op_sel_hi:[1,1,0]
	v_add_u32_e32 v10, 0x100, v10
	v_mov_b32_e32 v47, v5
	s_cmpk_lt_u32 s0, 0x78
	v_pk_add_f32 v[4:5], v[46:47], v[12:13]
	v_lshl_add_u64 v[12:13], v[2:3], 0, v[16:17]
	global_store_dwordx2 v[12:13], v[4:5], off
	v_pk_mul_f32 v[12:13], v[8:9], v[4:5]
	v_lshl_add_u64 v[16:17], v[2:3], 0, v[40:41]
	v_pk_fma_f32 v[14:15], v[6:7], v[4:5], v[12:13] op_sel:[0,0,1] op_sel_hi:[1,1,0] neg_lo:[0,0,1] neg_hi:[0,0,1]
	v_pk_fma_f32 v[4:5], v[6:7], v[4:5], v[12:13] op_sel:[0,0,1] op_sel_hi:[1,1,0]
	v_lshl_add_u64 v[12:13], v[2:3], 0, v[20:21]
	v_mov_b32_e32 v15, v5
	v_pk_add_f32 v[4:5], v[18:19], v[14:15]
	global_store_dwordx2 v[12:13], v[4:5], off
	v_pk_mul_f32 v[12:13], v[8:9], v[4:5]
	s_nop 0
	v_pk_fma_f32 v[14:15], v[6:7], v[4:5], v[12:13] op_sel:[0,0,1] op_sel_hi:[1,1,0] neg_lo:[0,0,1] neg_hi:[0,0,1]
	v_pk_fma_f32 v[4:5], v[6:7], v[4:5], v[12:13] op_sel:[0,0,1] op_sel_hi:[1,1,0]
	v_lshl_add_u64 v[12:13], v[2:3], 0, v[24:25]
	v_mov_b32_e32 v15, v5
	v_pk_add_f32 v[4:5], v[22:23], v[14:15]
	global_store_dwordx2 v[12:13], v[4:5], off
	v_pk_mul_f32 v[12:13], v[8:9], v[4:5]
	s_nop 0
	v_pk_fma_f32 v[14:15], v[6:7], v[4:5], v[12:13] op_sel:[0,0,1] op_sel_hi:[1,1,0] neg_lo:[0,0,1] neg_hi:[0,0,1]
	v_pk_fma_f32 v[4:5], v[6:7], v[4:5], v[12:13] op_sel:[0,0,1] op_sel_hi:[1,1,0]
	v_lshl_add_u64 v[12:13], v[2:3], 0, v[28:29]
	v_mov_b32_e32 v15, v5
	v_pk_add_f32 v[4:5], v[26:27], v[14:15]
	global_store_dwordx2 v[12:13], v[4:5], off
	v_pk_mul_f32 v[12:13], v[8:9], v[4:5]
	s_nop 0
	v_pk_fma_f32 v[14:15], v[6:7], v[4:5], v[12:13] op_sel:[0,0,1] op_sel_hi:[1,1,0] neg_lo:[0,0,1] neg_hi:[0,0,1]
	v_pk_fma_f32 v[4:5], v[6:7], v[4:5], v[12:13] op_sel:[0,0,1] op_sel_hi:[1,1,0]
	v_lshl_add_u64 v[12:13], v[2:3], 0, v[36:37]
	v_mov_b32_e32 v15, v5
	v_lshl_add_u64 v[4:5], v[2:3], 0, v[32:33]
	v_pk_add_f32 v[14:15], v[30:31], v[14:15]
	global_store_dwordx2 v[4:5], v[14:15], off
	v_pk_mul_f32 v[4:5], v[8:9], v[14:15]
	s_nop 0
	v_pk_fma_f32 v[18:19], v[6:7], v[14:15], v[4:5] op_sel:[0,0,1] op_sel_hi:[1,1,0]
	v_pk_fma_f32 v[4:5], v[6:7], v[14:15], v[4:5] op_sel:[0,0,1] op_sel_hi:[1,1,0] neg_lo:[0,0,1] neg_hi:[0,0,1]
	s_nop 0
	v_mov_b32_e32 v5, v19
	v_pk_add_f32 v[4:5], v[34:35], v[4:5]
	global_store_dwordx2 v[12:13], v[4:5], off
	v_pk_mul_f32 v[12:13], v[8:9], v[4:5]
	s_nop 0
	v_pk_fma_f32 v[14:15], v[6:7], v[4:5], v[12:13] op_sel:[0,0,1] op_sel_hi:[1,1,0]
	v_pk_fma_f32 v[4:5], v[6:7], v[4:5], v[12:13] op_sel:[0,0,1] op_sel_hi:[1,1,0] neg_lo:[0,0,1] neg_hi:[0,0,1]
	s_nop 0
	v_mov_b32_e32 v5, v15
	v_pk_add_f32 v[4:5], v[38:39], v[4:5]
	global_store_dwordx2 v[16:17], v[4:5], off
	v_pk_mul_f32 v[12:13], v[8:9], v[4:5]
	s_nop 0
	v_pk_fma_f32 v[14:15], v[6:7], v[4:5], v[12:13] op_sel:[0,0,1] op_sel_hi:[1,1,0]
	v_pk_fma_f32 v[4:5], v[6:7], v[4:5], v[12:13] op_sel:[0,0,1] op_sel_hi:[1,1,0] neg_lo:[0,0,1] neg_hi:[0,0,1]
	s_nop 0
	v_mov_b32_e32 v5, v15
	v_pk_add_f32 v[4:5], v[44:45], v[4:5]
	s_cbranch_scc1 .LBB0_424
	s_waitcnt vmcnt(0)
	v_add_u32_e32 v42, s91, v42
	s_movk_i32 s0, 0xfff
	v_cmp_lt_i32_e32 vcc, s0, v42
	s_or_b64 s[14:15], vcc, s[14:15]
	s_andn2_b64 exec, exec, s[14:15]
	s_cbranch_execnz .LBB0_423
